# v8 plus in-loop K/V LDS-DMA addressed as scalar base + lane offset (tile stepping on SALU)
# speedup vs baseline: 1.0489x; 1.0161x over previous
; #define lane lane_id()
; __device__ __forceinline__ void body(const unsigned char* Q8b, const unsigned char* K8h, const unsigned char* VT8h, const bf16_t* Gb, bf16_t* Ob, int seq, char* lds, const int wid, ...
;     ...
;   const char* Kg = (const char*)K8h + krow * 256 + kc * 16; const char* Vg = (const char*)VT8h + wid * 1024 + lane * 16;
;   const int ksw = (r32 >> 1) & 7, ko = r32 * 128, c00 = ((0 + hi * 2) ^ ksw) << 4, c01 = ((1 + hi * 2) ^ ksw) << 4, c10 = ((4 + hi * 2) ^ ksw) << 4, c11 = ((5 + hi * 2) ^ ksw) << 4;
;   const int vsw = (r32 >> 2) & 3, vo = r32 * 64, e0 = ((2 * hi) ^ vsw) << 4, e1 = ((2 * hi + 1) ^ vsw) << 4;
; __global__ void __launch_bounds__(512, 2) fwd_megakernel(Params p) {
;     ...
;             const size_t m0 = (size_t)b * SEQ + (size_t)qb * 256, qo = m0 * DM + h * HD, ko = (size_t)b * SEQ * KVD + (h >> 2) * HD;
;             const size_t m0n = (size_t)bn * SEQ + (size_t)qbn * 256, qon = m0n * DM + hn * HD, kon = (size_t)bn * SEQ * KVD + (hn >> 2) * HD;
;             att8::body(ws + WS_Q + qo, ws + WS_K + ko, ws + WS_V + (size_t)(b * 2 + (h >> 2)) * 128 * 8192, Gb + qo, Hb + qo, SEQ, (char*)lds, wave,
;                        qr, i > 0, hn_ok, ws + WS_Q + qon, ws + WS_K + kon, ws + WS_V + (size_t)(bn * 2 + (hn >> 2)) * 128 * 8192);
.LBB0_369:
	s_lshl_b32 s47, s50, 1
	s_add_i32 s58, s47, s45
	s_ashr_i32 s59, s58, 31
	s_lshl_b64 s[58:59], s[58:59], 20
	v_lshl_add_u64 v[2:3], s[48:49], 0, v[202:203]
	v_lshl_add_u64 v[220:221], v[2:3], 0, v[204:205]
	s_andn2_b64 vcc, exec, s[60:61]
	v_lshl_add_u64 v[222:223], v[206:207], 0, s[58:59]
	s_nop 0
	v_readfirstlane_b32 s94, v220
	v_readfirstlane_b32 s95, v221
	v_readfirstlane_b32 s96, v222
	v_readfirstlane_b32 s97, v223
	s_nop 3
	s_sub_u32 s94, s94, 0x80
	s_subb_u32 s95, s95, 0
	s_add_u32 s98, s94, 0xc000
	s_addc_u32 s99, s95, 0
	s_add_u32 s100, s96, 0x6000
	s_addc_u32 s101, s97, 0
	v_subrev_u32_e32 v192, s94, v220
	v_subrev_u32_e32 v193, s96, v222
	s_cbranch_vccnz .LBB0_371
	s_mov_b32 m0, s70
	v_lshl_add_u64 v[2:3], v[220:221], 0, s[38:39]
	global_load_lds_dwordx4 v[220:221], off
	s_mov_b32 m0, s68
	s_nop 0
	global_load_lds_dwordx4 v[222:223], off
	s_mov_b32 m0, s72
	s_nop 0
	global_load_lds_dwordx4 v[2:3], off
	v_lshl_add_u64 v[2:3], v[222:223], 0, s[40:41]
	s_mov_b32 m0, s74
	s_nop 0
	global_load_lds_dwordx4 v[2:3], off

; #define SBAR() __builtin_amdgcn_sched_barrier(0)
; #define DMA(slot, t) do { \
;     __builtin_amdgcn_global_load_lds((const unsigned*)(Kg + (long)(t) * (64 * 256)), (LAS unsigned*)(L3 + K_OFF + (slot) * SHM_T + wid * 1024), 16, 0, 0); \
;     __builtin_amdgcn_global_load_lds((const unsigned*)(Vg + (long)(t) * 8192), (LAS unsigned*)(L3 + (slot) * SHM_T + wid * 1024), 16, 0, 0); } while (0)
; #define QKT(P0, P1, b) qkt(P0, P1, nm, K_lds + (b) * SHM_T, qr, ko, c00, c01, c10, c11)
; #define PIPE1() do { SGB(0x100, 8); SGB(0x400, 4); SGB(0x008, 1); SGB(0x400, 4); SGB(0x008, 1); SGB(0x400, 4); SGB(0x008, 1); SGB(0x400, 4); SGB(0x008, 1); } while (0)
; #define HALF2(Y0, Y1, alY, b) do { PVL(b); const float pm_ = max32(Y0, Y1); adjustSM(Y0, Y1, nm, alY, pm_); SBAR(); \
;     PVM(); exp16(Y0); asm volatile("" : "+v"(Y0)); \
;     SGB(0x008, 1); SGB(0x400, 3); SGB(0x008, 1); SGB(0x400, 3); SGB(0x008, 1); SGB(0x400, 3); SGB(0x008, 1); SGB(0x400, 3); SGB(0x008, 1); SGB(0x400, 4); SBAR(); } while (0)
; __device__ __forceinline__ void body(const unsigned char* Q8b, const unsigned char* K8h, const unsigned char* VT8h, const bf16_t* Gb, bf16_t* Ob, int seq, char* lds, const int wid, ...
;     ...
;   for (int i = 0; i + 2 < NT; i += 2) {
;     SBAR(); QKT(pB0, pB1, (s0 + 1) & 3);
;     finishSM(pA0, pA1, pf); PIPE1(); SBAR();
;     DMA((s0 + 3) & 3, i + 3);
;     SBAR();
;     HALF2(pB0, pB1, alB, s0);
.Lstg_a2:
	s_add_i32 s45, s45, 2
	s_add_u32 s100, s100, 0x4000
	s_addc_u32 s101, s101, 0
	s_add_u32 s98, s98, 0x8000
	s_addc_u32 s99, s99, 0
	s_cmpk_gt_u32 s45, 0x7d
	s_cbranch_scc1 .LBB0_385
	s_branch .Lc2_374
.LBB0_374:
	ds_read_b128 v[2:5], v242 offset:40960
	ds_read_b128 v[6:9], v243 offset:40960
	ds_read_b128 v[128:131], v242 offset:45056
	ds_read_b128 v[132:135], v243 offset:45056
	ds_read_b128 v[194:197], v244 offset:40960
	ds_read_b128 v[198:201], v245 offset:40960
	ds_read_b128 v[246:249], v244 offset:45056
	ds_read_b128 v[250:253], v245 offset:45056
	v_exp_f32_e32 v1, v112
	v_exp_f32_e32 v10, v113
	v_exp_f32_e32 v11, v114
	v_exp_f32_e32 v12, v115
	s_waitcnt lgkmcnt(6)
	s_setprio 1
	v_mfma_scale_f32_32x32x64_f8f6f4 v[160:175], v[2:9], v[176:183], v[96:111], v240, v239 op_sel_hi:[0,0,0]
	v_exp_f32_e32 v6, v116
	v_exp_f32_e32 v7, v117
	v_exp_f32_e32 v8, v118
	v_exp_f32_e32 v9, v119
	v_cvt_pk_fp8_f32 v5, v6, v7
	v_cvt_pk_fp8_f32 v3, v1, v10
	v_cvt_pk_fp8_f32 v5, v8, v9 op_sel:[0,0,1]
	s_waitcnt lgkmcnt(4)
	v_mfma_scale_f32_32x32x64_f8f6f4 v[128:143], v[128:135], v[176:183], v[96:111], v240, v239 op_sel_hi:[0,0,0]
	v_exp_f32_e32 v13, v120
	v_exp_f32_e32 v14, v121
	v_exp_f32_e32 v15, v122
	v_exp_f32_e32 v112, v123
	v_cvt_pk_fp8_f32 v2, v144, v145
	v_cvt_pk_fp8_f32 v4, v148, v149
	v_cvt_pk_fp8_f32 v6, v152, v153
	v_cvt_pk_fp8_f32 v7, v13, v14
	v_cvt_pk_fp8_f32 v8, v156, v157
	v_cvt_pk_fp8_f32 v2, v146, v147 op_sel:[0,0,1]
	v_cvt_pk_fp8_f32 v3, v11, v12 op_sel:[0,0,1]
	v_cvt_pk_fp8_f32 v4, v150, v151 op_sel:[0,0,1]
	v_cvt_pk_fp8_f32 v6, v154, v155 op_sel:[0,0,1]
	v_cvt_pk_fp8_f32 v7, v15, v112 op_sel:[0,0,1]
	v_cvt_pk_fp8_f32 v8, v158, v159 op_sel:[0,0,1]
	s_waitcnt lgkmcnt(2)
	v_mfma_scale_f32_32x32x64_f8f6f4 v[160:175], v[194:201], v[184:191], v[160:175], v240, v239 op_sel_hi:[0,0,0]
	v_exp_f32_e32 v113, v124
	v_exp_f32_e32 v114, v125
	v_exp_f32_e32 v1, v126
	v_exp_f32_e32 v10, v127
	v_permlane32_swap_b32_e32 v2, v3
	v_cvt_pk_fp8_f32 v9, v113, v114
	v_permlane32_swap_b32_e32 v4, v5
	v_permlane32_swap_b32_e32 v6, v7
	v_cvt_pk_fp8_f32 v9, v1, v10 op_sel:[0,0,1]
	s_nop 1
	v_permlane32_swap_b32_e32 v8, v9
	s_waitcnt lgkmcnt(0)
	v_mfma_scale_f32_32x32x64_f8f6f4 v[128:143], v[246:253], v[184:191], v[128:143], v240, v239 op_sel_hi:[0,0,0]
	s_setprio 0
	s_add_i32 m0, s68, 0xe000
	s_nop 0
	global_load_lds_dwordx4 v192, s[98:99]
	s_add_i32 m0, s68, 0x6000
	s_nop 0
	global_load_lds_dwordx4 v193, s[100:101]
	ds_read_b128 v[194:197], v254
	ds_read_b128 v[148:151], v254 offset:2048
	ds_read_b128 v[198:201], v255
	ds_read_b128 v[152:155], v255 offset:2048
	ds_read_b128 v[120:123], v254 offset:4096
	ds_read_b128 v[112:115], v254 offset:6144
	ds_read_b128 v[124:127], v255 offset:4096
	ds_read_b128 v[116:119], v255 offset:6144
	v_max_f32_e32 v1, v160, v161
	v_max3_f32 v1, v1, v162, v163
	v_max3_f32 v1, v1, v164, v165
	v_max3_f32 v1, v1, v166, v167
	v_max3_f32 v1, v1, v168, v169
	v_max3_f32 v1, v1, v170, v171
	v_max3_f32 v1, v1, v172, v173
	v_max3_f32 v1, v1, v174, v175
	v_max3_f32 v1, v1, v128, v129
	v_max3_f32 v1, v1, v130, v131
	v_max3_f32 v1, v1, v132, v133
	v_max3_f32 v1, v1, v134, v135
	v_max3_f32 v1, v1, v136, v137
	v_max3_f32 v1, v1, v138, v139
	v_max3_f32 v1, v1, v140, v141
	v_max3_f32 v1, v1, v142, v143
	v_cmp_lt_f32_e32 vcc, s80, v1
	s_cbranch_vccnz .LBB0_383

; #define SBAR() __builtin_amdgcn_sched_barrier(0)
; #define DMA(slot, t) do { \
;     __builtin_amdgcn_global_load_lds((const unsigned*)(Kg + (long)(t) * (64 * 256)), (LAS unsigned*)(L3 + K_OFF + (slot) * SHM_T + wid * 1024), 16, 0, 0); \
;     __builtin_amdgcn_global_load_lds((const unsigned*)(Vg + (long)(t) * 8192), (LAS unsigned*)(L3 + (slot) * SHM_T + wid * 1024), 16, 0, 0); } while (0)
; #define QKT(P0, P1, b) qkt(P0, P1, nm, K_lds + (b) * SHM_T, qr, ko, c00, c01, c10, c11)
; #define PIPE1() do { SGB(0x100, 8); SGB(0x400, 4); SGB(0x008, 1); SGB(0x400, 4); SGB(0x008, 1); SGB(0x400, 4); SGB(0x008, 1); SGB(0x400, 4); SGB(0x008, 1); } while (0)
; __device__ __forceinline__ void body(const unsigned char* Q8b, const unsigned char* K8h, const unsigned char* VT8h, const bf16_t* Gb, bf16_t* Ob, int seq, char* lds, const int wid, ...
;     ...
;     SBAR(); QKT(pA0, pA1, (s0 + 2) & 3);
;     finishSM(pB0, pB1, pf); PIPE1(); SBAR();
;     { const int t4 = (i + 4 < NT) ? i + 4 : NT - 1; DMA(s0, t4); }
.Lstg_a1:
	ds_read_b128 v[2:5], v242 offset:49152
	ds_read_b128 v[6:9], v243 offset:49152
	ds_read_b128 v[112:115], v242 offset:53248
	ds_read_b128 v[116:119], v243 offset:53248
	ds_read_b128 v[194:197], v244 offset:49152
	ds_read_b128 v[198:201], v245 offset:49152
	ds_read_b128 v[246:249], v244 offset:53248
	ds_read_b128 v[250:253], v245 offset:53248
	v_exp_f32_e32 v1, v128
	v_exp_f32_e32 v10, v129
	v_exp_f32_e32 v11, v130
	v_exp_f32_e32 v12, v131
	s_waitcnt lgkmcnt(6)
	s_setprio 1
	v_mfma_scale_f32_32x32x64_f8f6f4 v[160:175], v[2:9], v[176:183], v[96:111], v240, v239 op_sel_hi:[0,0,0]
	v_exp_f32_e32 v6, v132
	v_exp_f32_e32 v7, v133
	v_exp_f32_e32 v8, v134
	v_exp_f32_e32 v9, v135
	v_cvt_pk_fp8_f32 v5, v6, v7
	v_cvt_pk_fp8_f32 v2, v144, v145
	v_cvt_pk_fp8_f32 v5, v8, v9 op_sel:[0,0,1]
	s_waitcnt lgkmcnt(4)
	v_mfma_scale_f32_32x32x64_f8f6f4 v[112:127], v[112:119], v[176:183], v[96:111], v240, v239 op_sel_hi:[0,0,0]
	v_exp_f32_e32 v13, v136
	v_exp_f32_e32 v14, v137
	v_exp_f32_e32 v15, v138
	v_exp_f32_e32 v128, v139
	v_cvt_pk_fp8_f32 v3, v1, v10
	v_cvt_pk_fp8_f32 v4, v148, v149
	v_cvt_pk_fp8_f32 v6, v152, v153
	v_cvt_pk_fp8_f32 v7, v13, v14
	v_cvt_pk_fp8_f32 v8, v156, v157
	v_cvt_pk_fp8_f32 v2, v146, v147 op_sel:[0,0,1]
	v_cvt_pk_fp8_f32 v3, v11, v12 op_sel:[0,0,1]
	v_cvt_pk_fp8_f32 v4, v150, v151 op_sel:[0,0,1]
	v_cvt_pk_fp8_f32 v6, v154, v155 op_sel:[0,0,1]
	v_cvt_pk_fp8_f32 v7, v15, v128 op_sel:[0,0,1]
	v_cvt_pk_fp8_f32 v8, v158, v159 op_sel:[0,0,1]
	s_waitcnt lgkmcnt(2)
	v_mfma_scale_f32_32x32x64_f8f6f4 v[160:175], v[194:201], v[184:191], v[160:175], v240, v239 op_sel_hi:[0,0,0]
	v_exp_f32_e32 v129, v140
	v_exp_f32_e32 v130, v141
	v_exp_f32_e32 v131, v142
	v_exp_f32_e32 v132, v143
	v_permlane32_swap_b32_e32 v2, v3
	v_cvt_pk_fp8_f32 v9, v129, v130
	v_permlane32_swap_b32_e32 v4, v5
	v_permlane32_swap_b32_e32 v6, v7
	v_cvt_pk_fp8_f32 v9, v131, v132 op_sel:[0,0,1]
	s_nop 1
	v_permlane32_swap_b32_e32 v8, v9
	s_waitcnt lgkmcnt(0)
	v_mfma_scale_f32_32x32x64_f8f6f4 v[112:127], v[246:253], v[184:191], v[112:127], v240, v239 op_sel_hi:[0,0,0]
	s_setprio 0
	s_min_u32 s36, s45, 0x7b
	s_add_i32 s56, s36, 4
	s_lshl_b32 s36, s56, 14
	s_add_i32 s57, s68, 0x0
	s_add_u32 s88, s94, s36
	s_addc_u32 s89, s95, 0
	s_add_i32 m0, s57, 0x8000
	s_lshl_b32 s36, s56, 13
	s_add_u32 s90, s96, s36
	s_addc_u32 s91, s97, 0
	global_load_lds_dwordx4 v192, s[88:89]
	s_mov_b32 m0, s57
	s_nop 0
	global_load_lds_dwordx4 v193, s[90:91]
	ds_read_b128 v[194:197], v254 offset:8192
	ds_read_b128 v[148:151], v254 offset:10240
	ds_read_b128 v[198:201], v255 offset:8192
	ds_read_b128 v[152:155], v255 offset:10240
	ds_read_b128 v[136:139], v254 offset:12288
	ds_read_b128 v[128:131], v254 offset:14336
	ds_read_b128 v[140:143], v255 offset:12288
	ds_read_b128 v[132:135], v255 offset:14336
	v_max_f32_e32 v1, v160, v161
	v_max3_f32 v1, v1, v162, v163
	v_max3_f32 v1, v1, v164, v165
	v_max3_f32 v1, v1, v166, v167
	v_max3_f32 v1, v1, v168, v169
	v_max3_f32 v1, v1, v170, v171
	v_max3_f32 v1, v1, v172, v173
	v_max3_f32 v1, v1, v174, v175
	v_max3_f32 v1, v1, v112, v113
	v_max3_f32 v1, v1, v114, v115
	v_max3_f32 v1, v1, v116, v117
	v_max3_f32 v1, v1, v118, v119
	v_max3_f32 v1, v1, v120, v121
	v_max3_f32 v1, v1, v122, v123
	v_max3_f32 v1, v1, v124, v125
	v_max3_f32 v1, v1, v126, v127
	v_cmp_lt_f32_e32 vcc, s80, v1
	s_cbranch_vccnz .LBB0_384

; #define SBAR() __builtin_amdgcn_sched_barrier(0)
; #define DMA(slot, t) do { \
;     __builtin_amdgcn_global_load_lds((const unsigned*)(Kg + (long)(t) * (64 * 256)), (LAS unsigned*)(L3 + K_OFF + (slot) * SHM_T + wid * 1024), 16, 0, 0); \
;     __builtin_amdgcn_global_load_lds((const unsigned*)(Vg + (long)(t) * 8192), (LAS unsigned*)(L3 + (slot) * SHM_T + wid * 1024), 16, 0, 0); } while (0)
; #define QKT(P0, P1, b) qkt(P0, P1, nm, K_lds + (b) * SHM_T, qr, ko, c00, c01, c10, c11)
; #define PIPE1() do { SGB(0x100, 8); SGB(0x400, 4); SGB(0x008, 1); SGB(0x400, 4); SGB(0x008, 1); SGB(0x400, 4); SGB(0x008, 1); SGB(0x400, 4); SGB(0x008, 1); } while (0)
; #define HALF2(Y0, Y1, alY, b) do { PVL(b); const float pm_ = max32(Y0, Y1); adjustSM(Y0, Y1, nm, alY, pm_); SBAR(); \
;     PVM(); exp16(Y0); asm volatile("" : "+v"(Y0)); \
;     SGB(0x008, 1); SGB(0x400, 3); SGB(0x008, 1); SGB(0x400, 3); SGB(0x008, 1); SGB(0x400, 3); SGB(0x008, 1); SGB(0x400, 3); SGB(0x008, 1); SGB(0x400, 4); SBAR(); } while (0)
; __device__ __forceinline__ void body(const unsigned char* Q8b, const unsigned char* K8h, const unsigned char* VT8h, const bf16_t* Gb, bf16_t* Ob, int seq, char* lds, const int wid, ...
;     ...
;     SBAR(); QKT(pB0, pB1, (s0 + 1) & 3);
;     finishSM(pA0, pA1, pf); PIPE1(); SBAR();
;     DMA((s0 + 3) & 3, i + 3);
;     SBAR();
;     HALF2(pB0, pB1, alB, s0);
.Lc2_374:
	ds_read_b128 v[2:5], v242 offset:57344
	ds_read_b128 v[6:9], v243 offset:57344
	ds_read_b128 v[128:131], v242 offset:61440
	ds_read_b128 v[132:135], v243 offset:61440
	ds_read_b128 v[194:197], v244 offset:57344
	ds_read_b128 v[198:201], v245 offset:57344
	ds_read_b128 v[246:249], v244 offset:61440
	ds_read_b128 v[250:253], v245 offset:61440
	v_exp_f32_e32 v1, v112
	v_exp_f32_e32 v10, v113
	v_exp_f32_e32 v11, v114
	v_exp_f32_e32 v12, v115
	s_waitcnt lgkmcnt(6)
	s_setprio 1
	v_mfma_scale_f32_32x32x64_f8f6f4 v[160:175], v[2:9], v[176:183], v[96:111], v240, v239 op_sel_hi:[0,0,0]
	v_exp_f32_e32 v6, v116
	v_exp_f32_e32 v7, v117
	v_exp_f32_e32 v8, v118
	v_exp_f32_e32 v9, v119
	v_cvt_pk_fp8_f32 v5, v6, v7
	v_cvt_pk_fp8_f32 v3, v1, v10
	v_cvt_pk_fp8_f32 v5, v8, v9 op_sel:[0,0,1]
	s_waitcnt lgkmcnt(4)
	v_mfma_scale_f32_32x32x64_f8f6f4 v[128:143], v[128:135], v[176:183], v[96:111], v240, v239 op_sel_hi:[0,0,0]
	v_exp_f32_e32 v13, v120
	v_exp_f32_e32 v14, v121
	v_exp_f32_e32 v15, v122
	v_exp_f32_e32 v112, v123
	v_cvt_pk_fp8_f32 v2, v144, v145
	v_cvt_pk_fp8_f32 v4, v148, v149
	v_cvt_pk_fp8_f32 v6, v152, v153
	v_cvt_pk_fp8_f32 v7, v13, v14
	v_cvt_pk_fp8_f32 v8, v156, v157
	v_cvt_pk_fp8_f32 v2, v146, v147 op_sel:[0,0,1]
	v_cvt_pk_fp8_f32 v3, v11, v12 op_sel:[0,0,1]
	v_cvt_pk_fp8_f32 v4, v150, v151 op_sel:[0,0,1]
	v_cvt_pk_fp8_f32 v6, v154, v155 op_sel:[0,0,1]
	v_cvt_pk_fp8_f32 v7, v15, v112 op_sel:[0,0,1]
	v_cvt_pk_fp8_f32 v8, v158, v159 op_sel:[0,0,1]
	s_waitcnt lgkmcnt(2)
	v_mfma_scale_f32_32x32x64_f8f6f4 v[160:175], v[194:201], v[184:191], v[160:175], v240, v239 op_sel_hi:[0,0,0]
	v_exp_f32_e32 v113, v124
	v_exp_f32_e32 v114, v125
	v_exp_f32_e32 v1, v126
	v_exp_f32_e32 v10, v127
	v_permlane32_swap_b32_e32 v2, v3
	v_cvt_pk_fp8_f32 v9, v113, v114
	v_permlane32_swap_b32_e32 v4, v5
	v_permlane32_swap_b32_e32 v6, v7
	v_cvt_pk_fp8_f32 v9, v1, v10 op_sel:[0,0,1]
	s_nop 1
	v_permlane32_swap_b32_e32 v8, v9
	s_waitcnt lgkmcnt(0)
	v_mfma_scale_f32_32x32x64_f8f6f4 v[128:143], v[246:253], v[184:191], v[128:143], v240, v239 op_sel_hi:[0,0,0]
	s_setprio 0
	s_add_i32 m0, s68, 0xa000
	s_nop 0
	global_load_lds_dwordx4 v192, s[98:99]
	s_add_i32 m0, s68, 0x2000
	s_nop 0
	global_load_lds_dwordx4 v193, s[100:101]
	ds_read_b128 v[194:197], v254 offset:16384
	ds_read_b128 v[148:151], v254 offset:18432
	ds_read_b128 v[198:201], v255 offset:16384
	ds_read_b128 v[152:155], v255 offset:18432
	ds_read_b128 v[120:123], v254 offset:20480
	ds_read_b128 v[112:115], v254 offset:22528
	ds_read_b128 v[124:127], v255 offset:20480
	ds_read_b128 v[116:119], v255 offset:22528
	v_max_f32_e32 v1, v160, v161
	v_max3_f32 v1, v1, v162, v163
	v_max3_f32 v1, v1, v164, v165
	v_max3_f32 v1, v1, v166, v167
	v_max3_f32 v1, v1, v168, v169
	v_max3_f32 v1, v1, v170, v171
	v_max3_f32 v1, v1, v172, v173
	v_max3_f32 v1, v1, v174, v175
	v_max3_f32 v1, v1, v128, v129
	v_max3_f32 v1, v1, v130, v131
	v_max3_f32 v1, v1, v132, v133
	v_max3_f32 v1, v1, v134, v135
	v_max3_f32 v1, v1, v136, v137
	v_max3_f32 v1, v1, v138, v139
	v_max3_f32 v1, v1, v140, v141
	v_max3_f32 v1, v1, v142, v143
	v_cmp_lt_f32_e32 vcc, s80, v1
	s_cbranch_vccnz .Lc2_383

; #define SBAR() __builtin_amdgcn_sched_barrier(0)
; #define DMA(slot, t) do { \
;     __builtin_amdgcn_global_load_lds((const unsigned*)(Kg + (long)(t) * (64 * 256)), (LAS unsigned*)(L3 + K_OFF + (slot) * SHM_T + wid * 1024), 16, 0, 0); \
;     __builtin_amdgcn_global_load_lds((const unsigned*)(Vg + (long)(t) * 8192), (LAS unsigned*)(L3 + (slot) * SHM_T + wid * 1024), 16, 0, 0); } while (0)
; #define QKT(P0, P1, b) qkt(P0, P1, nm, K_lds + (b) * SHM_T, qr, ko, c00, c01, c10, c11)
; #define PIPE1() do { SGB(0x100, 8); SGB(0x400, 4); SGB(0x008, 1); SGB(0x400, 4); SGB(0x008, 1); SGB(0x400, 4); SGB(0x008, 1); SGB(0x400, 4); SGB(0x008, 1); } while (0)
; __device__ __forceinline__ void body(const unsigned char* Q8b, const unsigned char* K8h, const unsigned char* VT8h, const bf16_t* Gb, bf16_t* Ob, int seq, char* lds, const int wid, ...
;     ...
;     SBAR(); QKT(pA0, pA1, (s0 + 2) & 3);
;     finishSM(pB0, pB1, pf); PIPE1(); SBAR();
;     { const int t4 = (i + 4 < NT) ? i + 4 : NT - 1; DMA(s0, t4); }
.Lc2stg_a1:
	ds_read_b128 v[2:5], v242 offset:32768
	ds_read_b128 v[6:9], v243 offset:32768
	ds_read_b128 v[112:115], v242 offset:36864
	ds_read_b128 v[116:119], v243 offset:36864
	ds_read_b128 v[194:197], v244 offset:32768
	ds_read_b128 v[198:201], v245 offset:32768
	ds_read_b128 v[246:249], v244 offset:36864
	ds_read_b128 v[250:253], v245 offset:36864
	v_exp_f32_e32 v1, v128
	v_exp_f32_e32 v10, v129
	v_exp_f32_e32 v11, v130
	v_exp_f32_e32 v12, v131
	s_waitcnt lgkmcnt(6)
	s_setprio 1
	v_mfma_scale_f32_32x32x64_f8f6f4 v[160:175], v[2:9], v[176:183], v[96:111], v240, v239 op_sel_hi:[0,0,0]
	v_exp_f32_e32 v6, v132
	v_exp_f32_e32 v7, v133
	v_exp_f32_e32 v8, v134
	v_exp_f32_e32 v9, v135
	v_cvt_pk_fp8_f32 v5, v6, v7
	v_cvt_pk_fp8_f32 v2, v144, v145
	v_cvt_pk_fp8_f32 v5, v8, v9 op_sel:[0,0,1]
	s_waitcnt lgkmcnt(4)
	v_mfma_scale_f32_32x32x64_f8f6f4 v[112:127], v[112:119], v[176:183], v[96:111], v240, v239 op_sel_hi:[0,0,0]
	v_exp_f32_e32 v13, v136
	v_exp_f32_e32 v14, v137
	v_exp_f32_e32 v15, v138
	v_exp_f32_e32 v128, v139
	v_cvt_pk_fp8_f32 v3, v1, v10
	v_cvt_pk_fp8_f32 v4, v148, v149
	v_cvt_pk_fp8_f32 v6, v152, v153
	v_cvt_pk_fp8_f32 v7, v13, v14
	v_cvt_pk_fp8_f32 v8, v156, v157
	v_cvt_pk_fp8_f32 v2, v146, v147 op_sel:[0,0,1]
	v_cvt_pk_fp8_f32 v3, v11, v12 op_sel:[0,0,1]
	v_cvt_pk_fp8_f32 v4, v150, v151 op_sel:[0,0,1]
	v_cvt_pk_fp8_f32 v6, v154, v155 op_sel:[0,0,1]
	v_cvt_pk_fp8_f32 v7, v15, v128 op_sel:[0,0,1]
	v_cvt_pk_fp8_f32 v8, v158, v159 op_sel:[0,0,1]
	s_waitcnt lgkmcnt(2)
	v_mfma_scale_f32_32x32x64_f8f6f4 v[160:175], v[194:201], v[184:191], v[160:175], v240, v239 op_sel_hi:[0,0,0]
	v_exp_f32_e32 v129, v140
	v_exp_f32_e32 v130, v141
	v_exp_f32_e32 v131, v142
	v_exp_f32_e32 v132, v143
	v_permlane32_swap_b32_e32 v2, v3
	v_cvt_pk_fp8_f32 v9, v129, v130
	v_permlane32_swap_b32_e32 v4, v5
	v_permlane32_swap_b32_e32 v6, v7
	v_cvt_pk_fp8_f32 v9, v131, v132 op_sel:[0,0,1]
	s_nop 1
	v_permlane32_swap_b32_e32 v8, v9
	s_waitcnt lgkmcnt(0)
	v_mfma_scale_f32_32x32x64_f8f6f4 v[112:127], v[246:253], v[184:191], v[112:127], v240, v239 op_sel_hi:[0,0,0]
	s_setprio 0
	s_min_u32 s36, s45, 0x7b
	s_add_i32 s56, s36, 4
	s_lshl_b32 s36, s56, 14
	s_add_i32 s57, s68, 0x4000
	s_add_u32 s88, s94, s36
	s_addc_u32 s89, s95, 0
	s_add_i32 m0, s57, 0x8000
	s_lshl_b32 s36, s56, 13
	s_add_u32 s90, s96, s36
	s_addc_u32 s91, s97, 0
	global_load_lds_dwordx4 v192, s[88:89]
	s_mov_b32 m0, s57
	s_nop 0
	global_load_lds_dwordx4 v193, s[90:91]
	ds_read_b128 v[194:197], v254 offset:24576
	ds_read_b128 v[148:151], v254 offset:26624
	ds_read_b128 v[198:201], v255 offset:24576
	ds_read_b128 v[152:155], v255 offset:26624
	ds_read_b128 v[136:139], v254 offset:28672
	ds_read_b128 v[128:131], v254 offset:30720
	ds_read_b128 v[140:143], v255 offset:28672
	ds_read_b128 v[132:135], v255 offset:30720
	v_max_f32_e32 v1, v160, v161
	v_max3_f32 v1, v1, v162, v163
	v_max3_f32 v1, v1, v164, v165
	v_max3_f32 v1, v1, v166, v167
	v_max3_f32 v1, v1, v168, v169
	v_max3_f32 v1, v1, v170, v171
	v_max3_f32 v1, v1, v172, v173
	v_max3_f32 v1, v1, v174, v175
	v_max3_f32 v1, v1, v112, v113
	v_max3_f32 v1, v1, v114, v115
	v_max3_f32 v1, v1, v116, v117
	v_max3_f32 v1, v1, v118, v119
	v_max3_f32 v1, v1, v120, v121
	v_max3_f32 v1, v1, v122, v123
	v_max3_f32 v1, v1, v124, v125
	v_max3_f32 v1, v1, v126, v127
	v_cmp_lt_f32_e32 vcc, s80, v1
	s_cbranch_vccnz .Lc2_384

; __global__ void __launch_bounds__(512, 2) fwd_megakernel(Params p) {
	.amdhsa_kernel _Z14fwd_megakernel6Params
		.amdhsa_group_segment_fixed_size 0
		.amdhsa_private_segment_fixed_size 0
		.amdhsa_kernarg_size 400
		.amdhsa_user_sgpr_count 2
		.amdhsa_user_sgpr_dispatch_ptr 0
		.amdhsa_user_sgpr_queue_ptr 0
		.amdhsa_user_sgpr_kernarg_segment_ptr 1
		.amdhsa_user_sgpr_dispatch_id 0
		.amdhsa_user_sgpr_kernarg_preload_length 0
		.amdhsa_user_sgpr_kernarg_preload_offset 0
		.amdhsa_user_sgpr_private_segment_size 0
		.amdhsa_uses_dynamic_stack 0
		.amdhsa_enable_private_segment 0
		.amdhsa_system_sgpr_workgroup_id_x 1
		.amdhsa_system_sgpr_workgroup_id_y 0
		.amdhsa_system_sgpr_workgroup_id_z 0
		.amdhsa_system_sgpr_workgroup_info 0
		.amdhsa_system_vgpr_workitem_id 0
		.amdhsa_next_free_vgpr 256
		.amdhsa_next_free_sgpr 102
		.amdhsa_accum_offset 256
		.amdhsa_reserve_vcc 1
		.amdhsa_float_round_mode_32 0
		.amdhsa_float_round_mode_16_64 0
		.amdhsa_float_denorm_mode_32 3
		.amdhsa_float_denorm_mode_16_64 3
		.amdhsa_dx10_clamp 1
		.amdhsa_ieee_mode 1
		.amdhsa_fp16_overflow 0
		.amdhsa_tg_split 0
		.amdhsa_exception_fp_ieee_invalid_op 0
		.amdhsa_exception_fp_denorm_src 0
		.amdhsa_exception_fp_ieee_div_zero 0
		.amdhsa_exception_fp_ieee_overflow 0
		.amdhsa_exception_fp_ieee_underflow 0
		.amdhsa_exception_fp_ieee_inexact 0
		.amdhsa_exception_int_div_zero 0
	.end_amdhsa_kernel

; __global__ void __launch_bounds__(512, 2) fwd_megakernel(Params p) {
amdhsa.kernels:
  - .agpr_count:     0
    .args:
      - .offset:         0
        .size:           144
        .value_kind:     by_value
      - .offset:         144
        .size:           4
        .value_kind:     hidden_block_count_x
      - .offset:         148
        .size:           4
        .value_kind:     hidden_block_count_y
      - .offset:         152
        .size:           4
        .value_kind:     hidden_block_count_z
      - .offset:         156
        .size:           2
        .value_kind:     hidden_group_size_x
      - .offset:         158
        .size:           2
        .value_kind:     hidden_group_size_y
      - .offset:         160
        .size:           2
        .value_kind:     hidden_group_size_z
      - .offset:         162
        .size:           2
        .value_kind:     hidden_remainder_x
      - .offset:         164
        .size:           2
        .value_kind:     hidden_remainder_y
      - .offset:         166
        .size:           2
        .value_kind:     hidden_remainder_z
      - .offset:         184
        .size:           8
        .value_kind:     hidden_global_offset_x
      - .offset:         192
        .size:           8
        .value_kind:     hidden_global_offset_y
      - .offset:         200
        .size:           8
        .value_kind:     hidden_global_offset_z
      - .offset:         208
        .size:           2
        .value_kind:     hidden_grid_dims
      - .offset:         264
        .size:           4
        .value_kind:     hidden_dynamic_lds_size
    .group_segment_fixed_size: 0
    .kernarg_segment_align: 8
    .kernarg_segment_size: 400
    .language:       OpenCL C
    .language_version:
      - 2
      - 0
    .max_flat_workgroup_size: 512
    .name:           _Z14fwd_megakernel6Params
    .private_segment_fixed_size: 0
    .sgpr_count:     108
    .sgpr_spill_count: 0
    .symbol:         _Z14fwd_megakernel6Params.kd
    .uniform_work_group_size: 1
    .uses_dynamic_stack: false
    .vgpr_count:     256
    .vgpr_spill_count: 0
    .wavefront_size: 64
